# retention chunk tail: gate / gain loads of the four 16-dim groups issued together into spare registers with counted waits
# speedup vs baseline: 1.0018x; 1.0018x over previous
; DEVI f32x4 mfma16(bf16x8 a, bf16x8 b, f32x4 c) { return __builtin_amdgcn_mfma_f32_16x16x32_bf16(a, b, c, 0, 0, 0); }
; DEVI float fexp2(float x) { return __builtin_amdgcn_exp2f(x); }
; template <int M> DEVI float shx(float v) { return __int_as_float(__builtin_amdgcn_ds_swizzle(__float_as_int(v), (M << 10) | 0x1f)); }
; DEVI float shx32(float v, int lane) { return __int_as_float(__builtin_amdgcn_ds_bpermute((lane ^ 32) << 2, __float_as_int(v))); }
; DEVI void ret_item(const Ctx& cx, const float* __restrict__ gn, const float* __restrict__ xfl, const float* __restrict__ g1, const float* __restrict__ winl, int b, int h, unsigned char* lds, int wv) {
;     ...
;       for (int ks = 0; ks < 2; ++ks) {
;         bf16x8 sf = *(const bf16x8*)(lds + RET_ST + (dvt * 16 + idx) * LDS_ROW + ks * 64 + quad * 16);
;         oi[dvt] = mfma16(sf, q[ks], oi[dvt]);
;       }
;     }
;     const float rd = fexp2((float)(i + 1) * lg);
; #pragma unroll
;     for (int dvt = 0; dvt < 4; ++dvt) o[dvt] += oi[dvt] * rd;
; #pragma unroll
;     for (int t = 0; t < 2; ++t) {
;       f32x4 nw = (f32x4){0.f, 0.f, 0.f, 0.f};
; #pragma unroll
;       for (int kc = 0; kc < 4; ++kc) {
;         bf16x8 vf = *(const bf16x8*)(lds + RET_VT + (et * 16 + idx) * RET_ROWT + kc * 64 + quad * 16);
;         bf16x8 kf = *(const bf16x8*)(lds + RET_KWT + ((dt0 + t) * 16 + idx) * RET_ROWT + kc * 64 + quad * 16);
;         nw = mfma16(vf, kf, nw);
;       }
;       st[t] = st[t] * cdecay + nw;
;     }
;     float sum = 0.f;
; #pragma unroll
;     for (int dvt = 0; dvt < 4; ++dvt) sum += o[dvt][0] + o[dvt][1] + o[dvt][2] + o[dvt][3];
;     sum += shx<16>(sum); sum += shx32(sum, quad * 16 + idx);
;     const float mu = sum * (1.f / 64.f);
;     float var = 0.f;
; #pragma unroll
;     for (int dvt = 0; dvt < 4; ++dvt)
; #pragma unroll
;       for (int j = 0; j < 4; ++j) { float d = o[dvt][j] - mu; var += d * d; }
;     var += shx<16>(var); var += shx32(var, quad * 16 + idx);
;     const float rstd = rsqrtf(var * (1.f / 64.f) + 1e-6f);
; #pragma unroll
;     for (int dvt = 0; dvt < 4; ++dvt) {
;       const int dv = dvt * 16 + quad * 4;
;       const u32x2 gw = *(const u32x2*)(cx.proj + tokrow * PS + C_RG + h * 64 + dv);
;       const float4 gg = *(const float4*)(gn + h * 64 + dv);
.LBB0_1295:
	s_or_b64 exec, exec, vcc
	ds_read_b128 v[0:3], v170 offset:57856
	ds_read_b128 v[4:7], v170 offset:57920
	v_pk_fma_f32 v[8:9], v[80:81], v[60:61], v[18:19]
	v_pk_fma_f32 v[18:19], v[78:79], v[58:59], v[16:17]
	v_pk_fma_f32 v[10:11], v[80:81], v[64:65], v[22:23]
	v_pk_fma_f32 v[16:17], v[78:79], v[62:63], v[20:21]
	v_mov_b32_e32 v77, v76
	v_mov_b32_e32 v129, v33
	v_ashrrev_i32_e32 v151, 31, v150
	s_waitcnt lgkmcnt(1)
	v_mfma_f32_16x16x32_bf16 v[0:3], v[0:3], v[38:41], 0
	v_mov_b32_e32 v137, v33
	v_mov_b32_e32 v139, v33
	v_mov_b32_e32 v141, v33
	v_lshl_add_u64 v[208:209], v[148:149], 0, v[128:129]
	v_lshl_add_u64 v[210:211], v[148:149], 0, v[136:137]
	v_lshl_add_u64 v[212:213], v[148:149], 0, v[138:139]
	v_lshl_add_u64 v[214:215], v[148:149], 0, v[140:141]
	global_load_dwordx2 v[184:185], v[208:209], off offset:3968
	global_load_dwordx4 v[192:195], v[110:111], off
	global_load_dwordx2 v[186:187], v[210:211], off offset:3968
	global_load_dwordx4 v[196:199], v[112:113], off
	global_load_dwordx2 v[188:189], v[212:213], off offset:3968
	global_load_dwordx4 v[200:203], v[114:115], off
	global_load_dwordx2 v[190:191], v[214:215], off offset:3968
	global_load_dwordx4 v[204:207], v[116:117], off
	s_waitcnt lgkmcnt(0)
	v_mfma_f32_16x16x32_bf16 v[0:3], v[4:7], v[34:37], v[0:3]
	v_fma_f32 v34, v80, v68, v26
	v_fma_f32 v35, v81, v69, v27
	v_pk_fma_f32 v[36:37], v[78:79], v[66:67], v[24:25]
	s_addk_i32 s2, 0x80
	s_cmpk_lg_i32 s2, 0x800
	s_nop 2
	v_pk_fma_f32 v[38:39], v[80:81], v[2:3], v[30:31]
	v_pk_fma_f32 v[40:41], v[78:79], v[0:1], v[28:29]
	ds_read_b128 v[0:3], v165 offset:35840
	ds_read_b128 v[4:7], v166 offset:18432
	ds_read_b128 v[12:15], v165 offset:35904
	ds_read_b128 v[20:23], v166 offset:18496
	s_waitcnt lgkmcnt(2)
	v_mfma_f32_16x16x32_bf16 v[4:7], v[0:3], v[4:7], 0
	s_waitcnt lgkmcnt(0)
	v_mfma_f32_16x16x32_bf16 v[4:7], v[12:15], v[20:23], v[4:7]
	ds_read_b128 v[20:23], v165 offset:35968
	ds_read_b128 v[24:27], v166 offset:18560
	s_waitcnt lgkmcnt(0)
	v_mfma_f32_16x16x32_bf16 v[4:7], v[20:23], v[24:27], v[4:7]
	ds_read_b128 v[24:27], v165 offset:36032
	ds_read_b128 v[28:31], v166 offset:18624
	s_waitcnt lgkmcnt(0)
	v_mfma_f32_16x16x32_bf16 v[4:7], v[24:27], v[28:31], v[4:7]
	s_nop 7
	v_pk_fma_f32 v[142:143], v[76:77], v[142:143], v[6:7]
	v_pk_fma_f32 v[74:75], v[82:83], v[74:75], v[4:5]
	ds_read_b128 v[4:7], v167 offset:18432
	s_waitcnt lgkmcnt(0)
	v_mfma_f32_16x16x32_bf16 v[0:3], v[0:3], v[4:7], 0
	ds_read_b128 v[4:7], v167 offset:18496
	s_waitcnt lgkmcnt(0)
	v_mfma_f32_16x16x32_bf16 v[0:3], v[12:15], v[4:7], v[0:3]
	ds_read_b128 v[4:7], v167 offset:18560
	s_waitcnt lgkmcnt(0)
	v_mfma_f32_16x16x32_bf16 v[0:3], v[20:23], v[4:7], v[0:3]
	ds_read_b128 v[4:7], v167 offset:18624
	v_lshlrev_b64 v[20:21], 11, v[150:151]
	s_waitcnt lgkmcnt(0)
	v_mfma_f32_16x16x32_bf16 v[0:3], v[24:27], v[4:7], v[0:3]
	s_nop 7
	v_pk_fma_f32 v[146:147], v[76:77], v[146:147], v[2:3]
	v_pk_fma_f32 v[144:145], v[82:83], v[144:145], v[0:1]
	v_mov_b32_e32 v0, v16
	v_mov_b32_e32 v1, v18
	v_mov_b32_e32 v2, v17
	v_mov_b32_e32 v3, v19
	v_pk_add_f32 v[0:1], v[0:1], v[2:3]
	v_mov_b32_e32 v2, v10
	v_mov_b32_e32 v3, v8
	v_pk_add_f32 v[0:1], v[2:3], v[0:1]
	v_mov_b32_e32 v2, v11
	v_mov_b32_e32 v3, v9
	v_pk_add_f32 v[0:1], v[2:3], v[0:1]
	v_mov_b32_e32 v2, v37
	v_add_f32_e32 v1, 0, v1
	v_add_f32_e32 v4, v0, v1
	v_mov_b32_e32 v0, v36
	v_mov_b32_e32 v1, v40
	v_mov_b32_e32 v3, v41
	v_pk_add_f32 v[0:1], v[0:1], v[2:3]
	v_mov_b32_e32 v2, v34
	v_mov_b32_e32 v3, v38
	v_pk_add_f32 v[0:1], v[2:3], v[0:1]
	v_mov_b32_e32 v2, v35
	v_mov_b32_e32 v3, v39
	v_pk_add_f32 v[0:1], v[2:3], v[0:1]
	s_nop 0
	v_add_f32_e32 v0, v0, v4
	v_add_f32_e32 v0, v0, v1
	ds_swizzle_b32 v1, v0 offset:swizzle(SWAP,16)
	s_waitcnt lgkmcnt(0)
	v_add_f32_e32 v0, v0, v1
	ds_bpermute_b32 v1, v131, v0
	s_waitcnt lgkmcnt(0)
	v_add_f32_e32 v1, v0, v1
	v_fmac_f32_e32 v19, 0xbc800000, v1
	v_fmamk_f32 v18, v1, 0xbc800000, v18
	v_mul_f32_e32 v4, v19, v19
	v_fmac_f32_e32 v4, v18, v18
	v_fmamk_f32 v8, v1, 0xbc800000, v8
	v_fmac_f32_e32 v4, v8, v8
	v_fmac_f32_e32 v9, 0xbc800000, v1
	v_fmac_f32_e32 v4, v9, v9
	v_fmamk_f32 v22, v1, 0xbc800000, v16
	v_fmac_f32_e32 v4, v22, v22
	v_fmac_f32_e32 v17, 0xbc800000, v1
	v_mul_f32_e32 v0, 0x3c800000, v1
	v_fmac_f32_e32 v4, v17, v17
	v_fmamk_f32 v10, v1, 0xbc800000, v10
	v_fmac_f32_e32 v4, v10, v10
	v_fmac_f32_e32 v11, 0xbc800000, v1
	v_pk_add_f32 v[14:15], v[36:37], v[0:1] op_sel_hi:[1,0] neg_lo:[0,1] neg_hi:[0,1]
	v_fmac_f32_e32 v4, v11, v11
	v_pk_mul_f32 v[2:3], v[14:15], v[14:15]
	s_nop 0
	v_add_f32_e32 v1, v2, v4
	v_add_f32_e32 v1, v3, v1
	v_pk_add_f32 v[12:13], v[34:35], v[0:1] op_sel_hi:[1,0] neg_lo:[0,1] neg_hi:[0,1]
	s_nop 0
	v_pk_mul_f32 v[2:3], v[12:13], v[12:13]
	s_nop 0
	v_add_f32_e32 v1, v2, v1
	v_add_f32_e32 v1, v3, v1
	v_pk_add_f32 v[6:7], v[40:41], v[0:1] op_sel_hi:[1,0] neg_lo:[0,1] neg_hi:[0,1]
	s_nop 0
	v_pk_mul_f32 v[2:3], v[6:7], v[6:7]
	s_nop 0
	v_add_f32_e32 v1, v2, v1
	v_pk_add_f32 v[4:5], v[38:39], v[0:1] op_sel_hi:[1,0] neg_lo:[0,1] neg_hi:[0,1]
	v_add_f32_e32 v2, v3, v1
	v_pk_mul_f32 v[0:1], v[4:5], v[4:5]
	s_nop 0
	v_add_f32_e32 v0, v0, v2
	v_add_f32_e32 v0, v1, v0
	ds_swizzle_b32 v1, v0 offset:swizzle(SWAP,16)
	s_waitcnt lgkmcnt(0)
	v_add_f32_e32 v0, v0, v1
	ds_bpermute_b32 v1, v131, v0
	s_waitcnt lgkmcnt(0)
	v_add_f32_e32 v0, v0, v1
	v_fmamk_f32 v0, v0, 0x3c800000, v224
	v_cmp_gt_f32_e32 vcc, s92, v0
	v_mul_f32_e32 v1, 0x4b800000, v0
	s_nop 0
	v_cndmask_b32_e32 v0, v0, v1, vcc
	v_rsq_f32_e32 v0, v0
	s_nop 0
	v_mul_f32_e32 v1, 0x45800000, v0
	v_cndmask_b32_e32 v16, v0, v1, vcc
	v_lshl_add_u64 v[0:1], v[148:149], 0, v[128:129]
	s_waitcnt vmcnt(6)
; DEVI void store_bf4(bf16_t* p, f32x4 v) { u32x2 w; w.x = pk2(v[0], v[1]); w.y = pk2(v[2], v[3]); *(u32x2*)p = w; }
; DEVI float sigmoidf(float x) { return 1.f / (1.f + __expf(-x)); }
; DEVI void ret_item(const Ctx& cx, const float* __restrict__ gn, const float* __restrict__ xfl, const float* __restrict__ g1, const float* __restrict__ winl, int b, int h, unsigned char* lds, int wv) {
;     ...
;     for (int dvt = 0; dvt < 4; ++dvt) {
;       const int dv = dvt * 16 + quad * 4;
;       const u32x2 gw = *(const u32x2*)(cx.proj + tokrow * PS + C_RG + h * 64 + dv);
;       const float4 gg = *(const float4*)(gn + h * 64 + dv);
;       float gt[4] = {__uint_as_float(gw.x << 16), __uint_as_float(gw.x & 0xffff0000u), __uint_as_float(gw.y << 16), __uint_as_float(gw.y & 0xffff0000u)};
;       float gnv[4] = {gg.x, gg.y, gg.z, gg.w};
;       f32x4 r;
; #pragma unroll
;       for (int j = 0; j < 4; ++j) r[j] = (o[dvt][j] - mu) * rstd * gnv[j] * (gt[j] * sigmoidf(gt[j]));
;       store_bf4(cx.mixed + tokrow * DM + 704 + h * 64 + dv, r);
	v_mov_b32_e32 v24, v184
	v_mov_b32_e32 v25, v185
	v_mov_b32_e32 v0, v192
	v_mov_b32_e32 v1, v193
	v_mov_b32_e32 v2, v194
	v_mov_b32_e32 v3, v195
	v_mul_f32_e32 v18, v18, v16
	v_mul_f32_e32 v22, v22, v16
	v_mul_f32_e32 v14, v14, v16
	v_mul_f32_e32 v6, v6, v16
	v_lshlrev_b32_e32 v23, 16, v24
	v_mul_f32_e32 v0, v0, v18
	v_mul_f32_e32 v18, 0xbfb8aa3b, v23
	v_exp_f32_e32 v18, v18
	v_and_b32_e32 v24, 0xffff0000, v24
	v_lshlrev_b32_e32 v26, 16, v25
	v_and_b32_e32 v25, 0xffff0000, v25
	v_add_f32_e32 v18, 1.0, v18
	v_div_scale_f32 v27, s[96:97], v18, v18, 1.0
	v_rcp_f32_e32 v28, v27
	s_nop 0
	v_fma_f32 v29, -v27, v28, 1.0
	v_fmac_f32_e32 v28, v29, v28
	v_div_scale_f32 v29, vcc, 1.0, v18, 1.0
	v_mul_f32_e32 v30, v29, v28
	v_fma_f32 v31, -v27, v30, v29
	v_fmac_f32_e32 v30, v31, v28
	v_fma_f32 v27, -v27, v30, v29
	v_div_fmas_f32 v27, v27, v28, v30
	v_div_fixup_f32 v18, v27, v18, 1.0
	v_mul_f32_e32 v18, v18, v23
	v_mul_f32_e32 v18, v18, v0
	v_mul_f32_e32 v0, v19, v16
	v_mul_f32_e32 v0, v1, v0
	v_mul_f32_e32 v1, 0xbfb8aa3b, v24
	v_exp_f32_e32 v1, v1
	s_nop 0
	v_add_f32_e32 v1, 1.0, v1
	v_div_scale_f32 v19, s[96:97], v1, v1, 1.0
	v_rcp_f32_e32 v23, v19
	s_nop 0
	v_fma_f32 v27, -v19, v23, 1.0
	v_fmac_f32_e32 v23, v27, v23
	v_div_scale_f32 v27, vcc, 1.0, v1, 1.0
	v_mul_f32_e32 v28, v27, v23
	v_fma_f32 v29, -v19, v28, v27
	v_fmac_f32_e32 v28, v29, v23
	v_fma_f32 v19, -v19, v28, v27
	v_div_fmas_f32 v19, v19, v23, v28
	v_div_fixup_f32 v1, v19, v1, 1.0
	v_mul_f32_e32 v1, v1, v24
	v_mul_f32_e32 v19, v1, v0
	v_mul_f32_e32 v1, 0xbfb8aa3b, v26
	v_exp_f32_e32 v1, v1
	v_mul_f32_e32 v0, v8, v16
	v_mul_f32_e32 v0, v2, v0
	v_add_f32_e32 v1, 1.0, v1
	v_div_scale_f32 v2, s[96:97], v1, v1, 1.0
	v_rcp_f32_e32 v8, v2
	s_nop 0
	v_fma_f32 v23, -v2, v8, 1.0
	v_fmac_f32_e32 v8, v23, v8
	v_div_scale_f32 v23, vcc, 1.0, v1, 1.0
	v_mul_f32_e32 v24, v23, v8
	v_fma_f32 v27, -v2, v24, v23
	v_fmac_f32_e32 v24, v27, v8
	v_fma_f32 v2, -v2, v24, v23
	v_div_fmas_f32 v2, v2, v8, v24
	v_div_fixup_f32 v1, v2, v1, 1.0
	v_mul_f32_e32 v1, v1, v26
	v_mul_f32_e32 v23, v1, v0
	v_mul_f32_e32 v1, 0xbfb8aa3b, v25
	v_exp_f32_e32 v1, v1
	v_mul_f32_e32 v0, v9, v16
	v_mul_f32_e32 v0, v3, v0
	v_add_f32_e32 v1, 1.0, v1
	v_div_scale_f32 v2, s[96:97], v1, v1, 1.0
	v_rcp_f32_e32 v3, v2
	s_nop 0
	v_fma_f32 v8, -v2, v3, 1.0
	v_fmac_f32_e32 v3, v8, v3
	v_div_scale_f32 v8, vcc, 1.0, v1, 1.0
	v_mul_f32_e32 v9, v8, v3
	v_fma_f32 v24, -v2, v9, v8
	v_fmac_f32_e32 v9, v24, v3
	v_fma_f32 v2, -v2, v9, v8
	v_div_fmas_f32 v2, v2, v3, v9
	v_div_fixup_f32 v1, v2, v1, 1.0
	v_mul_f32_e32 v1, v1, v25
	v_lshl_add_u64 v[8:9], s[86:87], 0, v[20:21]
	v_mul_f32_e32 v3, v1, v0
	v_lshl_add_u64 v[0:1], v[8:9], 0, v[128:129]
	v_cvt_pk_bf16_f32 v2, v18, v19
	v_cvt_pk_bf16_f32 v3, v23, v3
	global_store_dwordx2 v[0:1], v[2:3], off offset:1408
	v_lshl_add_u64 v[0:1], v[148:149], 0, v[136:137]
	s_waitcnt vmcnt(5)
	v_mov_b32_e32 v18, v186
	v_mov_b32_e32 v19, v187
	v_mov_b32_e32 v0, v196
	v_mov_b32_e32 v1, v197
	v_mov_b32_e32 v2, v198
	v_mov_b32_e32 v3, v199
	v_lshlrev_b32_e32 v20, 16, v18
	v_mul_f32_e32 v0, v0, v22
	v_mul_f32_e32 v22, 0xbfb8aa3b, v20
	v_exp_f32_e32 v22, v22
	v_and_b32_e32 v18, 0xffff0000, v18
	v_lshlrev_b32_e32 v21, 16, v19
	v_and_b32_e32 v19, 0xffff0000, v19
	v_add_f32_e32 v22, 1.0, v22
	v_div_scale_f32 v23, s[96:97], v22, v22, 1.0
	v_rcp_f32_e32 v24, v23
	s_nop 0
	v_fma_f32 v25, -v23, v24, 1.0
	v_fmac_f32_e32 v24, v25, v24
	v_div_scale_f32 v25, vcc, 1.0, v22, 1.0
	v_mul_f32_e32 v26, v25, v24
	v_fma_f32 v27, -v23, v26, v25
	v_fmac_f32_e32 v26, v27, v24
	v_fma_f32 v23, -v23, v26, v25
	v_div_fmas_f32 v23, v23, v24, v26
	v_div_fixup_f32 v22, v23, v22, 1.0
	v_mul_f32_e32 v20, v22, v20
	v_mul_f32_e32 v20, v20, v0
	v_mul_f32_e32 v0, v17, v16
	v_mul_f32_e32 v0, v1, v0
	v_mul_f32_e32 v1, 0xbfb8aa3b, v18
	v_exp_f32_e32 v1, v1
	s_nop 0
	v_add_f32_e32 v1, 1.0, v1
	v_div_scale_f32 v17, s[96:97], v1, v1, 1.0
	v_rcp_f32_e32 v22, v17
	s_nop 0
	v_fma_f32 v23, -v17, v22, 1.0
	v_fmac_f32_e32 v22, v23, v22
	v_div_scale_f32 v23, vcc, 1.0, v1, 1.0
	v_mul_f32_e32 v24, v23, v22
	v_fma_f32 v25, -v17, v24, v23
	v_fmac_f32_e32 v24, v25, v22
	v_fma_f32 v17, -v17, v24, v23
	v_div_fmas_f32 v17, v17, v22, v24
	v_div_fixup_f32 v1, v17, v1, 1.0
	v_mul_f32_e32 v1, v1, v18
	v_mul_f32_e32 v17, v1, v0
	v_mul_f32_e32 v1, 0xbfb8aa3b, v21
	v_exp_f32_e32 v1, v1
	v_mul_f32_e32 v0, v10, v16
	v_mul_f32_e32 v0, v2, v0
	v_add_f32_e32 v1, 1.0, v1
	v_div_scale_f32 v2, s[96:97], v1, v1, 1.0
	v_rcp_f32_e32 v10, v2
	s_nop 0
	v_fma_f32 v18, -v2, v10, 1.0
	v_fmac_f32_e32 v10, v18, v10
	v_div_scale_f32 v18, vcc, 1.0, v1, 1.0
	v_mul_f32_e32 v22, v18, v10
	v_fma_f32 v23, -v2, v22, v18
	v_fmac_f32_e32 v22, v23, v10
	v_fma_f32 v2, -v2, v22, v18
	v_div_fmas_f32 v2, v2, v10, v22
	v_div_fixup_f32 v1, v2, v1, 1.0
	v_mul_f32_e32 v1, v1, v21
	v_mul_f32_e32 v10, v1, v0
	v_mul_f32_e32 v1, 0xbfb8aa3b, v19
	v_exp_f32_e32 v1, v1
	v_mul_f32_e32 v0, v11, v16
	v_mul_f32_e32 v0, v3, v0
	v_add_f32_e32 v1, 1.0, v1
	v_div_scale_f32 v2, s[96:97], v1, v1, 1.0
	v_rcp_f32_e32 v3, v2
	s_nop 0
	v_fma_f32 v11, -v2, v3, 1.0
	v_fmac_f32_e32 v3, v11, v3
	v_div_scale_f32 v11, vcc, 1.0, v1, 1.0
	v_mul_f32_e32 v18, v11, v3
	v_fma_f32 v21, -v2, v18, v11
	v_fmac_f32_e32 v18, v21, v3
	v_fma_f32 v2, -v2, v18, v11
	v_div_fmas_f32 v2, v2, v3, v18
	v_div_fixup_f32 v1, v2, v1, 1.0
	v_mul_f32_e32 v1, v1, v19
	v_mul_f32_e32 v3, v1, v0
	v_lshl_add_u64 v[0:1], v[8:9], 0, v[136:137]
	v_cvt_pk_bf16_f32 v2, v20, v17
	v_cvt_pk_bf16_f32 v3, v10, v3
	global_store_dwordx2 v[0:1], v[2:3], off offset:1408
	v_lshl_add_u64 v[0:1], v[148:149], 0, v[138:139]
	s_waitcnt vmcnt(4)
; DEVI void store_bf4(bf16_t* p, f32x4 v) { u32x2 w; w.x = pk2(v[0], v[1]); w.y = pk2(v[2], v[3]); *(u32x2*)p = w; }
; DEVI float sigmoidf(float x) { return 1.f / (1.f + __expf(-x)); }
; DEVI void ret_item(const Ctx& cx, const float* __restrict__ gn, const float* __restrict__ xfl, const float* __restrict__ g1, const float* __restrict__ winl, int b, int h, unsigned char* lds, int wv) {
;     ...
;   for (int ci = 0; ci < 16; ++ci) {
;     ...
;     for (int dvt = 0; dvt < 4; ++dvt) {
;       const int dv = dvt * 16 + quad * 4;
;       const u32x2 gw = *(const u32x2*)(cx.proj + tokrow * PS + C_RG + h * 64 + dv);
;       const float4 gg = *(const float4*)(gn + h * 64 + dv);
;       float gt[4] = {__uint_as_float(gw.x << 16), __uint_as_float(gw.x & 0xffff0000u), __uint_as_float(gw.y << 16), __uint_as_float(gw.y & 0xffff0000u)};
;       float gnv[4] = {gg.x, gg.y, gg.z, gg.w};
;       f32x4 r;
; #pragma unroll
;       for (int j = 0; j < 4; ++j) r[j] = (o[dvt][j] - mu) * rstd * gnv[j] * (gt[j] * sigmoidf(gt[j]));
;       store_bf4(cx.mixed + tokrow * DM + 704 + h * 64 + dv, r);
;     }
	v_mov_b32_e32 v10, v188
	v_mov_b32_e32 v11, v189
	v_mov_b32_e32 v0, v200
	v_mov_b32_e32 v1, v201
	v_mov_b32_e32 v2, v202
	v_mov_b32_e32 v3, v203
	v_lshlrev_b32_e32 v17, 16, v10
	v_mul_f32_e32 v0, v0, v14
	v_mul_f32_e32 v14, 0xbfb8aa3b, v17
	v_exp_f32_e32 v14, v14
	v_and_b32_e32 v10, 0xffff0000, v10
	v_lshlrev_b32_e32 v18, 16, v11
	v_and_b32_e32 v11, 0xffff0000, v11
	v_add_f32_e32 v14, 1.0, v14
	v_div_scale_f32 v19, s[96:97], v14, v14, 1.0
	v_rcp_f32_e32 v20, v19
	s_nop 0
	v_fma_f32 v21, -v19, v20, 1.0
	v_fmac_f32_e32 v20, v21, v20
	v_div_scale_f32 v21, vcc, 1.0, v14, 1.0
	v_mul_f32_e32 v22, v21, v20
	v_fma_f32 v23, -v19, v22, v21
	v_fmac_f32_e32 v22, v23, v20
	v_fma_f32 v19, -v19, v22, v21
	v_div_fmas_f32 v19, v19, v20, v22
	v_div_fixup_f32 v14, v19, v14, 1.0
	v_mul_f32_e32 v14, v14, v17
	v_mul_f32_e32 v14, v14, v0
	v_mul_f32_e32 v0, v15, v16
	v_mul_f32_e32 v0, v1, v0
	v_mul_f32_e32 v1, 0xbfb8aa3b, v10
	v_exp_f32_e32 v1, v1
	s_nop 0
	v_add_f32_e32 v1, 1.0, v1
	v_div_scale_f32 v15, s[96:97], v1, v1, 1.0
	v_rcp_f32_e32 v17, v15
	s_nop 0
	v_fma_f32 v19, -v15, v17, 1.0
	v_fmac_f32_e32 v17, v19, v17
	v_div_scale_f32 v19, vcc, 1.0, v1, 1.0
	v_mul_f32_e32 v20, v19, v17
	v_fma_f32 v21, -v15, v20, v19
	v_fmac_f32_e32 v20, v21, v17
	v_fma_f32 v15, -v15, v20, v19
	v_div_fmas_f32 v15, v15, v17, v20
	v_div_fixup_f32 v1, v15, v1, 1.0
	v_mul_f32_e32 v1, v1, v10
	v_mul_f32_e32 v10, v1, v0
	v_mul_f32_e32 v1, 0xbfb8aa3b, v18
	v_exp_f32_e32 v1, v1
	v_mul_f32_e32 v0, v12, v16
	v_mul_f32_e32 v0, v2, v0
	v_add_f32_e32 v1, 1.0, v1
	v_div_scale_f32 v2, s[96:97], v1, v1, 1.0
	v_rcp_f32_e32 v12, v2
	s_nop 0
	v_fma_f32 v15, -v2, v12, 1.0
	v_fmac_f32_e32 v12, v15, v12
	v_div_scale_f32 v15, vcc, 1.0, v1, 1.0
	v_mul_f32_e32 v17, v15, v12
	v_fma_f32 v19, -v2, v17, v15
	v_fmac_f32_e32 v17, v19, v12
	v_fma_f32 v2, -v2, v17, v15
	v_div_fmas_f32 v2, v2, v12, v17
	v_div_fixup_f32 v1, v2, v1, 1.0
	v_mul_f32_e32 v1, v1, v18
	v_mul_f32_e32 v12, v1, v0
	v_mul_f32_e32 v1, 0xbfb8aa3b, v11
	v_exp_f32_e32 v1, v1
	v_mul_f32_e32 v0, v13, v16
	v_mul_f32_e32 v0, v3, v0
	v_add_f32_e32 v1, 1.0, v1
	v_div_scale_f32 v2, s[96:97], v1, v1, 1.0
	v_rcp_f32_e32 v3, v2
	s_nop 0
	v_fma_f32 v13, -v2, v3, 1.0
	v_fmac_f32_e32 v3, v13, v3
	v_div_scale_f32 v13, vcc, 1.0, v1, 1.0
	v_mul_f32_e32 v15, v13, v3
	v_fma_f32 v17, -v2, v15, v13
	v_fmac_f32_e32 v15, v17, v3
	v_fma_f32 v2, -v2, v15, v13
	v_div_fmas_f32 v2, v2, v3, v15
	v_div_fixup_f32 v1, v2, v1, 1.0
	v_mul_f32_e32 v1, v1, v11
	v_mul_f32_e32 v3, v1, v0
	v_lshl_add_u64 v[0:1], v[8:9], 0, v[138:139]
	v_cvt_pk_bf16_f32 v2, v14, v10
	v_cvt_pk_bf16_f32 v3, v12, v3
	global_store_dwordx2 v[0:1], v[2:3], off offset:1408
	v_lshl_add_u64 v[0:1], v[148:149], 0, v[140:141]
	s_waitcnt vmcnt(3)
	v_mov_b32_e32 v10, v190
	v_mov_b32_e32 v11, v191
	v_mov_b32_e32 v0, v204
	v_mov_b32_e32 v1, v205
	v_mov_b32_e32 v2, v206
	v_mov_b32_e32 v3, v207
	v_lshlrev_b32_e32 v12, 16, v10
	v_mul_f32_e32 v0, v0, v6
	v_mul_f32_e32 v6, 0xbfb8aa3b, v12
	v_exp_f32_e32 v6, v6
	v_and_b32_e32 v10, 0xffff0000, v10
	v_lshlrev_b32_e32 v13, 16, v11
	v_and_b32_e32 v11, 0xffff0000, v11
	v_add_f32_e32 v6, 1.0, v6
	v_div_scale_f32 v14, s[96:97], v6, v6, 1.0
	v_rcp_f32_e32 v15, v14
	s_nop 0
	v_fma_f32 v17, -v14, v15, 1.0
	v_fmac_f32_e32 v15, v17, v15
	v_div_scale_f32 v17, vcc, 1.0, v6, 1.0
	v_mul_f32_e32 v18, v17, v15
	v_fma_f32 v19, -v14, v18, v17
	v_fmac_f32_e32 v18, v19, v15
	v_fma_f32 v14, -v14, v18, v17
	v_div_fmas_f32 v14, v14, v15, v18
	v_div_fixup_f32 v6, v14, v6, 1.0
	v_mul_f32_e32 v6, v6, v12
	v_mul_f32_e32 v6, v0, v6
	v_mul_f32_e32 v0, v7, v16
	v_mul_f32_e32 v0, v1, v0
	v_mul_f32_e32 v1, 0xbfb8aa3b, v10
	v_exp_f32_e32 v1, v1
	s_nop 0
	v_add_f32_e32 v1, 1.0, v1
	v_div_scale_f32 v7, s[96:97], v1, v1, 1.0
	v_rcp_f32_e32 v12, v7
	s_nop 0
	v_fma_f32 v14, -v7, v12, 1.0
	v_fmac_f32_e32 v12, v14, v12
	v_div_scale_f32 v14, vcc, 1.0, v1, 1.0
	v_mul_f32_e32 v15, v14, v12
	v_fma_f32 v17, -v7, v15, v14
	v_fmac_f32_e32 v15, v17, v12
	v_fma_f32 v7, -v7, v15, v14
	v_div_fmas_f32 v7, v7, v12, v15
	v_div_fixup_f32 v1, v7, v1, 1.0
	v_mul_f32_e32 v1, v1, v10
	v_mul_f32_e32 v7, v0, v1
	v_mul_f32_e32 v1, 0xbfb8aa3b, v13
	v_exp_f32_e32 v1, v1
	v_mul_f32_e32 v0, v4, v16
	v_mul_f32_e32 v0, v2, v0
	v_add_f32_e32 v1, 1.0, v1
	v_div_scale_f32 v2, s[96:97], v1, v1, 1.0
	v_rcp_f32_e32 v4, v2
	s_nop 0
	v_fma_f32 v10, -v2, v4, 1.0
	v_fmac_f32_e32 v4, v10, v4
	v_div_scale_f32 v10, vcc, 1.0, v1, 1.0
	v_mul_f32_e32 v12, v10, v4
	v_fma_f32 v14, -v2, v12, v10
	v_fmac_f32_e32 v12, v14, v4
	v_fma_f32 v2, -v2, v12, v10
	v_div_fmas_f32 v2, v2, v4, v12
	v_div_fixup_f32 v1, v2, v1, 1.0
	v_mul_f32_e32 v1, v1, v13
	v_mul_f32_e32 v4, v0, v1
	v_mul_f32_e32 v1, 0xbfb8aa3b, v11
	v_exp_f32_e32 v1, v1
	v_mul_f32_e32 v0, v5, v16
	v_mul_f32_e32 v0, v0, v3
	v_add_f32_e32 v1, 1.0, v1
	v_div_scale_f32 v2, s[96:97], v1, v1, 1.0
	v_rcp_f32_e32 v3, v2
	s_mov_b64 s[96:97], 0x100
	v_lshl_add_u64 v[124:125], v[124:125], 0, s[96:97]
	v_lshl_add_u64 v[126:127], v[126:127], 0, s[96:97]
	v_fma_f32 v5, -v2, v3, 1.0
	v_fmac_f32_e32 v3, v5, v3
	v_div_scale_f32 v5, vcc, 1.0, v1, 1.0
	v_mul_f32_e32 v10, v5, v3
	v_fma_f32 v12, -v2, v10, v5
	v_fmac_f32_e32 v10, v12, v3
	v_fma_f32 v2, -v2, v10, v5
	v_div_fmas_f32 v2, v2, v3, v10
	v_div_fixup_f32 v1, v2, v1, 1.0
	v_mul_f32_e32 v1, v1, v11
	v_mul_f32_e32 v3, v0, v1
	v_lshl_add_u64 v[0:1], v[8:9], 0, v[140:141]
	v_cvt_pk_bf16_f32 v2, v6, v7
	v_cvt_pk_bf16_f32 v3, v4, v3
	global_store_dwordx2 v[0:1], v[2:3], off offset:1408
	s_cbranch_scc0 .LBB0_1344
